# v50: prep - the four positional-encoding dot-product items moved from workgroups 0..3 (which also carry S5 tables) to workgroups 252..255
# baseline (speedup 1.0000x reference)
.LBB0_943:
	v_readlane_b32 s66, v254, 3
	v_readlane_b32 s67, v254, 4
	s_load_dwordx2 s[62:63], s[66:67], 0xe0
	v_readlane_b32 s0, v254, 0
	v_and_b32_e32 v8, 63, v86
	s_cmp_eq_u32 s18, 0x100
	s_cbranch_scc0 .Lcpe_norm
	s_sub_i32 s0, s0, 0xfc
	s_cmp_lt_i32 s0, 0
	s_cbranch_scc1 .LBB0_950
.Lcpe_norm:
	s_cmp_gt_i32 s0, 3
	v_ashrrev_i32_e32 v9, 6, v86
	s_cbranch_scc1 .LBB0_950
	v_readlane_b32 s4, v254, 13
	v_readlane_b32 s5, v254, 14
	v_lshlrev_b32_e32 v2, 8, v9
	v_mov_b32_e32 v0, s4
	v_mov_b32_e32 v1, s5
	v_ashrrev_i32_e32 v3, 31, v2
	v_lshl_add_u64 v[0:1], v[2:3], 2, v[0:1]
	v_lshlrev_b64 v[2:3], 8, v[2:3]
	v_readlane_b32 s2, v254, 40
	v_readlane_b32 s6, v254, 15
	v_readlane_b32 s7, v254, 16
	v_lshl_or_b32 v2, v8, 2, v2
	v_readlane_b32 s3, v254, 41
	s_add_u32 s2, s2, 0xd600000
	v_lshl_add_u64 v[2:3], s[6:7], 0, v[2:3]
	s_mov_b64 s[4:5], 0x800
	s_addc_u32 s3, s3, 0
	v_lshl_add_u32 v10, v86, 2, 0
	v_cmp_gt_i32_e32 vcc, 64, v86
	v_lshl_add_u64 v[2:3], v[2:3], 0, s[4:5]
	s_mov_b64 s[4:5], 0x1000
	s_branch .LBB0_946
